# attA work queues: when a pop finds its queue dry, thread 0 reads all 8 queue counters in one round trip and broadcasts a dry-queue bitmask; the queue walk skips flagged queues instead of paying an ato
# speedup vs baseline: 1.0078x; 1.0078x over previous
; __global__ void __launch_bounds__(NTHR, 2) fwd_kernel(Ptrs P) {
;     ...
; #pragma unroll 1
;         for (int qx = 0; qx < 8; ++qx) {
;             const int xq = (xcc + qx) & 7;
;             const int h0 = xq, h1 = 7 - xq, h2 = (xq + 4) & 7, h3 = 7 - h2;
;             const int r0 = (h1 > h0) + (h2 > h0) + (h3 > h0), r1 = (h0 > h1) + (h2 > h1) + (h3 > h1), r2 = (h0 > h2) + (h1 > h2) + (h3 > h2);
; #pragma unroll 1
;             for (;;) {
;                 if (tid == 0) *qslot = (int)atomicAdd((unsigned*)(ws + 256 + 256 * xq), 1u);
;                 __syncthreads();
;                 const int idx = *qslot;
;                 __syncthreads();
;                 if (idx >= 128) break;
;                 const int k = idx >> 5, qblk = 31 - (idx & 31);
.LBB0_381:
	s_cmp_eq_u32 s51, 7
	s_cbranch_scc1 .LBB0_424
	s_and_saveexec_b64 s[2:3], s[8:9]
	s_cbranch_execz .La_qs_bcast
	global_load_dword v2, v1, s[68:69] offset:256 sc1
	global_load_dword v3, v1, s[68:69] offset:512 sc1
	global_load_dword v4, v1, s[68:69] offset:768 sc1
	global_load_dword v5, v1, s[68:69] offset:1024 sc1
	global_load_dword v6, v1, s[68:69] offset:1280 sc1
	global_load_dword v7, v1, s[68:69] offset:1536 sc1
	global_load_dword v8, v1, s[68:69] offset:1792 sc1
	global_load_dword v9, v1, s[68:69] offset:2048 sc1
	v_mov_b32_e32 v10, 0
	s_waitcnt vmcnt(0)
	v_lshrrev_b32_e32 v2, 7, v2
	v_min_u32_e32 v2, 1, v2
	v_lshl_or_b32 v10, v2, 0, v10
	v_lshrrev_b32_e32 v3, 7, v3
	v_min_u32_e32 v3, 1, v3
	v_lshl_or_b32 v10, v3, 1, v10
	v_lshrrev_b32_e32 v4, 7, v4
	v_min_u32_e32 v4, 1, v4
	v_lshl_or_b32 v10, v4, 2, v10
	v_lshrrev_b32_e32 v5, 7, v5
	v_min_u32_e32 v5, 1, v5
	v_lshl_or_b32 v10, v5, 3, v10
	v_lshrrev_b32_e32 v6, 7, v6
	v_min_u32_e32 v6, 1, v6
	v_lshl_or_b32 v10, v6, 4, v10
	v_lshrrev_b32_e32 v7, 7, v7
	v_min_u32_e32 v7, 1, v7
	v_lshl_or_b32 v10, v7, 5, v10
	v_lshrrev_b32_e32 v8, 7, v8
	v_min_u32_e32 v8, 1, v8
	v_lshl_or_b32 v10, v8, 6, v10
	v_lshrrev_b32_e32 v9, 7, v9
	v_min_u32_e32 v9, 1, v9
	v_lshl_or_b32 v10, v9, 7, v10
	v_mov_b32_e32 v11, s50
	ds_write_b32 v11, v10
.La_qs_bcast:
	s_or_b64 exec, exec, s[2:3]
	v_mov_b32_e32 v0, s50
	s_waitcnt lgkmcnt(0)
	s_barrier
	ds_read_b32 v0, v0
	s_waitcnt lgkmcnt(0)
	s_barrier
	v_readfirstlane_b32 s4, v0
.La_qs_next:
	s_add_i32 s51, s51, 1
	s_cmp_lg_u32 s51, 8
	s_cbranch_scc0 .LBB0_424
	s_add_i32 s2, s51, s33
	s_and_b32 s2, s2, 7
	s_bitcmp1_b32 s4, s2
	s_cbranch_scc1 .La_qs_next
